# phase 9 final-norm replaced by hand-written 3-row-deep pipelined loop with nt on x and D1 loads and out stores
# speedup vs baseline: 1.0306x; 1.0073x over previous
.LBB0_1451:
	s_cmp_lt_i32 s22, 10
	s_cselect_b64 s[0:1], -1, 0
	s_cmp_gt_i32 s23, 9
	s_cselect_b64 s[2:3], -1, 0
	s_and_b64 s[0:1], s[0:1], s[2:3]
	s_andn2_b64 vcc, exec, s[0:1]
	s_cbranch_vccnz .LBB0_1477
	s_mov_b64 s[4:5], exec
	s_waitcnt vmcnt(0) lgkmcnt(0)
	v_readfirstlane_b32 s16, v209
	s_lshl_b32 s14, s96, 3
	s_add_u32 s14, s14, s16
	s_lshl_b32 s15, s82, 3
	s_cmp_ge_u32 s14, 0x8000
	s_cbranch_scc1 .LBB0_1465
	v_and_b32_e32 v142, 63, v208
	v_lshlrev_b32_e32 v143, 3, v142
	v_lshlrev_b32_e32 v142, 4, v142
	global_load_dwordx4 v[112:115], v142, s[42:43] offset:0
	global_load_dwordx4 v[116:119], v142, s[42:43] offset:1024
	global_load_dwordx4 v[120:123], v142, s[42:43] offset:2048
	global_load_dwordx4 v[124:127], v142, s[42:43] offset:3072
	v_mov_b32_e32 v140, 0x3a800000
	v_mov_b32_e32 v141, 0x358637bd
	s_lshl_b32 s16, s14, 12
	s_add_u32 s0, s36, s16
	s_addc_u32 s1, s37, 0
	s_add_u32 s8, s18, s16
	s_addc_u32 s9, s19, 0
	s_lshl_b32 s16, s14, 11
	s_add_u32 s2, s20, s16
	s_addc_u32 s3, s21, 0
	s_add_u32 s2, s2, 0x15f60000
	s_addc_u32 s3, s3, 0
	s_add_u32 s6, s20, s16
	s_addc_u32 s7, s21, 0
	s_add_u32 s6, s6, 0x4f60000
	s_addc_u32 s7, s7, 0
	s_lshl_b32 s10, s15, 12
	s_lshl_b32 s12, s15, 11
	global_load_dwordx4 v[16:19], v142, s[0:1] nt
	global_load_dwordx4 v[20:23], v142, s[0:1] offset:1024 nt
	global_load_dwordx4 v[24:27], v142, s[0:1] offset:2048 nt
	global_load_dwordx4 v[28:31], v142, s[0:1] offset:3072 nt
	global_load_dwordx2 v[32:33], v143, s[2:3] nt
	global_load_dwordx2 v[34:35], v143, s[2:3] offset:512 nt
	global_load_dwordx2 v[36:37], v143, s[2:3] offset:1024 nt
	global_load_dwordx2 v[38:39], v143, s[2:3] offset:1536 nt
	global_load_dwordx2 v[40:41], v143, s[6:7]
	global_load_dwordx2 v[42:43], v143, s[6:7] offset:512
	global_load_dwordx2 v[44:45], v143, s[6:7] offset:1024
	global_load_dwordx2 v[46:47], v143, s[6:7] offset:1536
	s_add_u32 s0, s0, s10
	s_addc_u32 s1, s1, 0
	s_add_u32 s2, s2, s12
	s_addc_u32 s3, s3, 0
	s_add_u32 s6, s6, s12
	s_addc_u32 s7, s7, 0
	s_add_u32 s14, s14, s15
	s_cmp_ge_u32 s14, 0x8000
	s_cbranch_scc0 .Lfnorm_two
	s_waitcnt vmcnt(0)
	v_lshlrev_b32_e32 v128, 16, v32
	v_and_b32_e32 v129, 0xffff0000, v32
	v_lshlrev_b32_e32 v130, 16, v33
	v_and_b32_e32 v131, 0xffff0000, v33
	v_pk_add_f32 v[16:17], v[16:17], v[128:129]
	v_pk_add_f32 v[18:19], v[18:19], v[130:131]
	v_lshlrev_b32_e32 v132, 16, v34
	v_and_b32_e32 v133, 0xffff0000, v34
	v_lshlrev_b32_e32 v134, 16, v35
	v_and_b32_e32 v135, 0xffff0000, v35
	v_pk_add_f32 v[20:21], v[20:21], v[132:133]
	v_pk_add_f32 v[22:23], v[22:23], v[134:135]
	v_lshlrev_b32_e32 v128, 16, v36
	v_and_b32_e32 v129, 0xffff0000, v36
	v_lshlrev_b32_e32 v130, 16, v37
	v_and_b32_e32 v131, 0xffff0000, v37
	v_pk_add_f32 v[24:25], v[24:25], v[128:129]
	v_pk_add_f32 v[26:27], v[26:27], v[130:131]
	v_lshlrev_b32_e32 v132, 16, v38
	v_and_b32_e32 v133, 0xffff0000, v38
	v_lshlrev_b32_e32 v134, 16, v39
	v_and_b32_e32 v135, 0xffff0000, v39
	v_pk_add_f32 v[28:29], v[28:29], v[132:133]
	v_pk_add_f32 v[30:31], v[30:31], v[134:135]
	v_lshlrev_b32_e32 v128, 16, v40
	v_and_b32_e32 v129, 0xffff0000, v40
	v_lshlrev_b32_e32 v130, 16, v41
	v_and_b32_e32 v131, 0xffff0000, v41
	v_pk_add_f32 v[16:17], v[16:17], v[128:129]
	v_pk_add_f32 v[18:19], v[18:19], v[130:131]
	v_lshlrev_b32_e32 v132, 16, v42
	v_and_b32_e32 v133, 0xffff0000, v42
	v_lshlrev_b32_e32 v134, 16, v43
	v_and_b32_e32 v135, 0xffff0000, v43
	v_pk_add_f32 v[20:21], v[20:21], v[132:133]
	v_pk_add_f32 v[22:23], v[22:23], v[134:135]
	v_lshlrev_b32_e32 v128, 16, v44
	v_and_b32_e32 v129, 0xffff0000, v44
	v_lshlrev_b32_e32 v130, 16, v45
	v_and_b32_e32 v131, 0xffff0000, v45
	v_pk_add_f32 v[24:25], v[24:25], v[128:129]
	v_pk_add_f32 v[26:27], v[26:27], v[130:131]
	v_lshlrev_b32_e32 v132, 16, v46
	v_and_b32_e32 v133, 0xffff0000, v46
	v_lshlrev_b32_e32 v134, 16, v47
	v_and_b32_e32 v135, 0xffff0000, v47
	v_pk_add_f32 v[28:29], v[28:29], v[132:133]
	v_pk_add_f32 v[30:31], v[30:31], v[134:135]
	v_pk_mul_f32 v[136:137], v[16:17], v[16:17]
	v_pk_mul_f32 v[128:129], v[18:19], v[18:19]
	v_pk_fma_f32 v[136:137], v[20:21], v[20:21], v[136:137]
	v_pk_fma_f32 v[128:129], v[22:23], v[22:23], v[128:129]
	v_pk_fma_f32 v[136:137], v[24:25], v[24:25], v[136:137]
	v_pk_fma_f32 v[128:129], v[26:27], v[26:27], v[128:129]
	v_pk_fma_f32 v[136:137], v[28:29], v[28:29], v[136:137]
	v_pk_fma_f32 v[128:129], v[30:31], v[30:31], v[128:129]
	v_pk_add_f32 v[136:137], v[136:137], v[128:129]
	s_nop 0
	v_add_f32_e32 v136, v136, v137
	s_nop 1
	v_add_f32_dpp v136, v136, v136 quad_perm:[1,0,3,2] row_mask:0xf bank_mask:0xf
	s_nop 1
	v_add_f32_dpp v136, v136, v136 quad_perm:[2,3,0,1] row_mask:0xf bank_mask:0xf
	s_nop 1
	v_add_f32_dpp v136, v136, v136 row_half_mirror row_mask:0xf bank_mask:0xf
	s_nop 1
	v_add_f32_dpp v136, v136, v136 row_mirror row_mask:0xf bank_mask:0xf
	s_nop 1
	v_add_f32_dpp v136, v136, v136 row_bcast:15 row_mask:0xa bank_mask:0xf
	s_nop 1
	v_add_f32_dpp v136, v136, v136 row_bcast:31 row_mask:0xc bank_mask:0xf
	s_nop 1
	v_readlane_b32 s16, v136, 63
	s_nop 3
	v_fma_f32 v138, s16, v140, v141
	v_rsq_f32_e32 v138, v138
	s_nop 0
	v_mov_b32_e32 v139, v138
	v_pk_mul_f32 v[16:17], v[16:17], v[138:139]
	v_pk_mul_f32 v[18:19], v[18:19], v[138:139]
	v_pk_mul_f32 v[20:21], v[20:21], v[138:139]
	v_pk_mul_f32 v[22:23], v[22:23], v[138:139]
	v_pk_mul_f32 v[24:25], v[24:25], v[138:139]
	v_pk_mul_f32 v[26:27], v[26:27], v[138:139]
	v_pk_mul_f32 v[28:29], v[28:29], v[138:139]
	v_pk_mul_f32 v[30:31], v[30:31], v[138:139]
	v_pk_mul_f32 v[16:17], v[16:17], v[112:113]
	v_pk_mul_f32 v[18:19], v[18:19], v[114:115]
	v_pk_mul_f32 v[20:21], v[20:21], v[116:117]
	v_pk_mul_f32 v[22:23], v[22:23], v[118:119]
	v_pk_mul_f32 v[24:25], v[24:25], v[120:121]
	v_pk_mul_f32 v[26:27], v[26:27], v[122:123]
	v_pk_mul_f32 v[28:29], v[28:29], v[124:125]
	v_pk_mul_f32 v[30:31], v[30:31], v[126:127]
	global_store_dwordx4 v142, v[16:19], s[8:9] nt
	global_store_dwordx4 v142, v[20:23], s[8:9] offset:1024 nt
	global_store_dwordx4 v142, v[24:27], s[8:9] offset:2048 nt
	global_store_dwordx4 v142, v[28:31], s[8:9] offset:3072 nt
	s_add_u32 s8, s8, s10
	s_addc_u32 s9, s9, 0
	s_branch .Lfnorm_done
.Lfnorm_two:
	global_load_dwordx4 v[48:51], v142, s[0:1] nt
	global_load_dwordx4 v[52:55], v142, s[0:1] offset:1024 nt
	global_load_dwordx4 v[56:59], v142, s[0:1] offset:2048 nt
	global_load_dwordx4 v[60:63], v142, s[0:1] offset:3072 nt
	global_load_dwordx2 v[64:65], v143, s[2:3] nt
	global_load_dwordx2 v[66:67], v143, s[2:3] offset:512 nt
	global_load_dwordx2 v[68:69], v143, s[2:3] offset:1024 nt
	global_load_dwordx2 v[70:71], v143, s[2:3] offset:1536 nt
	global_load_dwordx2 v[72:73], v143, s[6:7]
	global_load_dwordx2 v[74:75], v143, s[6:7] offset:512
	global_load_dwordx2 v[76:77], v143, s[6:7] offset:1024
	global_load_dwordx2 v[78:79], v143, s[6:7] offset:1536
	s_add_u32 s0, s0, s10
	s_addc_u32 s1, s1, 0
	s_add_u32 s2, s2, s12
	s_addc_u32 s3, s3, 0
	s_add_u32 s6, s6, s12
	s_addc_u32 s7, s7, 0
	s_add_u32 s14, s14, s15
.Lfnorm_loop:
	s_cmp_ge_u32 s14, 0x8000
	s_cbranch_scc1 .Lfnorm_drain0
	global_load_dwordx4 v[80:83], v142, s[0:1] nt
	global_load_dwordx4 v[84:87], v142, s[0:1] offset:1024 nt
	global_load_dwordx4 v[88:91], v142, s[0:1] offset:2048 nt
	global_load_dwordx4 v[92:95], v142, s[0:1] offset:3072 nt
	global_load_dwordx2 v[96:97], v143, s[2:3] nt
	global_load_dwordx2 v[98:99], v143, s[2:3] offset:512 nt
	global_load_dwordx2 v[100:101], v143, s[2:3] offset:1024 nt
	global_load_dwordx2 v[102:103], v143, s[2:3] offset:1536 nt
	global_load_dwordx2 v[104:105], v143, s[6:7]
	global_load_dwordx2 v[106:107], v143, s[6:7] offset:512
	global_load_dwordx2 v[108:109], v143, s[6:7] offset:1024
	global_load_dwordx2 v[110:111], v143, s[6:7] offset:1536
	s_add_u32 s0, s0, s10
	s_addc_u32 s1, s1, 0
	s_add_u32 s2, s2, s12
	s_addc_u32 s3, s3, 0
	s_add_u32 s6, s6, s12
	s_addc_u32 s7, s7, 0
	s_add_u32 s14, s14, s15
	s_waitcnt vmcnt(24)
	v_lshlrev_b32_e32 v128, 16, v32
	v_and_b32_e32 v129, 0xffff0000, v32
	v_lshlrev_b32_e32 v130, 16, v33
	v_and_b32_e32 v131, 0xffff0000, v33
	v_pk_add_f32 v[16:17], v[16:17], v[128:129]
	v_pk_add_f32 v[18:19], v[18:19], v[130:131]
	v_lshlrev_b32_e32 v132, 16, v34
	v_and_b32_e32 v133, 0xffff0000, v34
	v_lshlrev_b32_e32 v134, 16, v35
	v_and_b32_e32 v135, 0xffff0000, v35
	v_pk_add_f32 v[20:21], v[20:21], v[132:133]
	v_pk_add_f32 v[22:23], v[22:23], v[134:135]
	v_lshlrev_b32_e32 v128, 16, v36
	v_and_b32_e32 v129, 0xffff0000, v36
	v_lshlrev_b32_e32 v130, 16, v37
	v_and_b32_e32 v131, 0xffff0000, v37
	v_pk_add_f32 v[24:25], v[24:25], v[128:129]
	v_pk_add_f32 v[26:27], v[26:27], v[130:131]
	v_lshlrev_b32_e32 v132, 16, v38
	v_and_b32_e32 v133, 0xffff0000, v38
	v_lshlrev_b32_e32 v134, 16, v39
	v_and_b32_e32 v135, 0xffff0000, v39
	v_pk_add_f32 v[28:29], v[28:29], v[132:133]
	v_pk_add_f32 v[30:31], v[30:31], v[134:135]
	v_lshlrev_b32_e32 v128, 16, v40
	v_and_b32_e32 v129, 0xffff0000, v40
	v_lshlrev_b32_e32 v130, 16, v41
	v_and_b32_e32 v131, 0xffff0000, v41
	v_pk_add_f32 v[16:17], v[16:17], v[128:129]
	v_pk_add_f32 v[18:19], v[18:19], v[130:131]
	v_lshlrev_b32_e32 v132, 16, v42
	v_and_b32_e32 v133, 0xffff0000, v42
	v_lshlrev_b32_e32 v134, 16, v43
	v_and_b32_e32 v135, 0xffff0000, v43
	v_pk_add_f32 v[20:21], v[20:21], v[132:133]
	v_pk_add_f32 v[22:23], v[22:23], v[134:135]
	v_lshlrev_b32_e32 v128, 16, v44
	v_and_b32_e32 v129, 0xffff0000, v44
	v_lshlrev_b32_e32 v130, 16, v45
	v_and_b32_e32 v131, 0xffff0000, v45
	v_pk_add_f32 v[24:25], v[24:25], v[128:129]
	v_pk_add_f32 v[26:27], v[26:27], v[130:131]
	v_lshlrev_b32_e32 v132, 16, v46
	v_and_b32_e32 v133, 0xffff0000, v46
	v_lshlrev_b32_e32 v134, 16, v47
	v_and_b32_e32 v135, 0xffff0000, v47
	v_pk_add_f32 v[28:29], v[28:29], v[132:133]
	v_pk_add_f32 v[30:31], v[30:31], v[134:135]
	v_pk_mul_f32 v[136:137], v[16:17], v[16:17]
	v_pk_mul_f32 v[128:129], v[18:19], v[18:19]
	v_pk_fma_f32 v[136:137], v[20:21], v[20:21], v[136:137]
	v_pk_fma_f32 v[128:129], v[22:23], v[22:23], v[128:129]
	v_pk_fma_f32 v[136:137], v[24:25], v[24:25], v[136:137]
	v_pk_fma_f32 v[128:129], v[26:27], v[26:27], v[128:129]
	v_pk_fma_f32 v[136:137], v[28:29], v[28:29], v[136:137]
	v_pk_fma_f32 v[128:129], v[30:31], v[30:31], v[128:129]
	v_pk_add_f32 v[136:137], v[136:137], v[128:129]
	s_nop 0
	v_add_f32_e32 v136, v136, v137
	s_nop 1
	v_add_f32_dpp v136, v136, v136 quad_perm:[1,0,3,2] row_mask:0xf bank_mask:0xf
	s_nop 1
	v_add_f32_dpp v136, v136, v136 quad_perm:[2,3,0,1] row_mask:0xf bank_mask:0xf
	s_nop 1
	v_add_f32_dpp v136, v136, v136 row_half_mirror row_mask:0xf bank_mask:0xf
	s_nop 1
	v_add_f32_dpp v136, v136, v136 row_mirror row_mask:0xf bank_mask:0xf
	s_nop 1
	v_add_f32_dpp v136, v136, v136 row_bcast:15 row_mask:0xa bank_mask:0xf
	s_nop 1
	v_add_f32_dpp v136, v136, v136 row_bcast:31 row_mask:0xc bank_mask:0xf
	s_nop 1
	v_readlane_b32 s16, v136, 63
	s_nop 3
	v_fma_f32 v138, s16, v140, v141
	v_rsq_f32_e32 v138, v138
	s_nop 0
	v_mov_b32_e32 v139, v138
	v_pk_mul_f32 v[16:17], v[16:17], v[138:139]
	v_pk_mul_f32 v[18:19], v[18:19], v[138:139]
	v_pk_mul_f32 v[20:21], v[20:21], v[138:139]
	v_pk_mul_f32 v[22:23], v[22:23], v[138:139]
	v_pk_mul_f32 v[24:25], v[24:25], v[138:139]
	v_pk_mul_f32 v[26:27], v[26:27], v[138:139]
	v_pk_mul_f32 v[28:29], v[28:29], v[138:139]
	v_pk_mul_f32 v[30:31], v[30:31], v[138:139]
	v_pk_mul_f32 v[16:17], v[16:17], v[112:113]
	v_pk_mul_f32 v[18:19], v[18:19], v[114:115]
	v_pk_mul_f32 v[20:21], v[20:21], v[116:117]
	v_pk_mul_f32 v[22:23], v[22:23], v[118:119]
	v_pk_mul_f32 v[24:25], v[24:25], v[120:121]
	v_pk_mul_f32 v[26:27], v[26:27], v[122:123]
	v_pk_mul_f32 v[28:29], v[28:29], v[124:125]
	v_pk_mul_f32 v[30:31], v[30:31], v[126:127]
	global_store_dwordx4 v142, v[16:19], s[8:9] nt
	global_store_dwordx4 v142, v[20:23], s[8:9] offset:1024 nt
	global_store_dwordx4 v142, v[24:27], s[8:9] offset:2048 nt
	global_store_dwordx4 v142, v[28:31], s[8:9] offset:3072 nt
	s_add_u32 s8, s8, s10
	s_addc_u32 s9, s9, 0
	s_cmp_ge_u32 s14, 0x8000
	s_cbranch_scc1 .Lfnorm_drain1
	global_load_dwordx4 v[16:19], v142, s[0:1] nt
	global_load_dwordx4 v[20:23], v142, s[0:1] offset:1024 nt
	global_load_dwordx4 v[24:27], v142, s[0:1] offset:2048 nt
	global_load_dwordx4 v[28:31], v142, s[0:1] offset:3072 nt
	global_load_dwordx2 v[32:33], v143, s[2:3] nt
	global_load_dwordx2 v[34:35], v143, s[2:3] offset:512 nt
	global_load_dwordx2 v[36:37], v143, s[2:3] offset:1024 nt
	global_load_dwordx2 v[38:39], v143, s[2:3] offset:1536 nt
	global_load_dwordx2 v[40:41], v143, s[6:7]
	global_load_dwordx2 v[42:43], v143, s[6:7] offset:512
	global_load_dwordx2 v[44:45], v143, s[6:7] offset:1024
	global_load_dwordx2 v[46:47], v143, s[6:7] offset:1536
	s_add_u32 s0, s0, s10
	s_addc_u32 s1, s1, 0
	s_add_u32 s2, s2, s12
	s_addc_u32 s3, s3, 0
	s_add_u32 s6, s6, s12
	s_addc_u32 s7, s7, 0
	s_add_u32 s14, s14, s15
	s_waitcnt vmcnt(24)
	v_lshlrev_b32_e32 v128, 16, v64
	v_and_b32_e32 v129, 0xffff0000, v64
	v_lshlrev_b32_e32 v130, 16, v65
	v_and_b32_e32 v131, 0xffff0000, v65
	v_pk_add_f32 v[48:49], v[48:49], v[128:129]
	v_pk_add_f32 v[50:51], v[50:51], v[130:131]
	v_lshlrev_b32_e32 v132, 16, v66
	v_and_b32_e32 v133, 0xffff0000, v66
	v_lshlrev_b32_e32 v134, 16, v67
	v_and_b32_e32 v135, 0xffff0000, v67
	v_pk_add_f32 v[52:53], v[52:53], v[132:133]
	v_pk_add_f32 v[54:55], v[54:55], v[134:135]
	v_lshlrev_b32_e32 v128, 16, v68
	v_and_b32_e32 v129, 0xffff0000, v68
	v_lshlrev_b32_e32 v130, 16, v69
	v_and_b32_e32 v131, 0xffff0000, v69
	v_pk_add_f32 v[56:57], v[56:57], v[128:129]
	v_pk_add_f32 v[58:59], v[58:59], v[130:131]
	v_lshlrev_b32_e32 v132, 16, v70
	v_and_b32_e32 v133, 0xffff0000, v70
	v_lshlrev_b32_e32 v134, 16, v71
	v_and_b32_e32 v135, 0xffff0000, v71
	v_pk_add_f32 v[60:61], v[60:61], v[132:133]
	v_pk_add_f32 v[62:63], v[62:63], v[134:135]
	v_lshlrev_b32_e32 v128, 16, v72
	v_and_b32_e32 v129, 0xffff0000, v72
	v_lshlrev_b32_e32 v130, 16, v73
	v_and_b32_e32 v131, 0xffff0000, v73
	v_pk_add_f32 v[48:49], v[48:49], v[128:129]
	v_pk_add_f32 v[50:51], v[50:51], v[130:131]
	v_lshlrev_b32_e32 v132, 16, v74
	v_and_b32_e32 v133, 0xffff0000, v74
	v_lshlrev_b32_e32 v134, 16, v75
	v_and_b32_e32 v135, 0xffff0000, v75
	v_pk_add_f32 v[52:53], v[52:53], v[132:133]
	v_pk_add_f32 v[54:55], v[54:55], v[134:135]
	v_lshlrev_b32_e32 v128, 16, v76
	v_and_b32_e32 v129, 0xffff0000, v76
	v_lshlrev_b32_e32 v130, 16, v77
	v_and_b32_e32 v131, 0xffff0000, v77
	v_pk_add_f32 v[56:57], v[56:57], v[128:129]
	v_pk_add_f32 v[58:59], v[58:59], v[130:131]
	v_lshlrev_b32_e32 v132, 16, v78
	v_and_b32_e32 v133, 0xffff0000, v78
	v_lshlrev_b32_e32 v134, 16, v79
	v_and_b32_e32 v135, 0xffff0000, v79
	v_pk_add_f32 v[60:61], v[60:61], v[132:133]
	v_pk_add_f32 v[62:63], v[62:63], v[134:135]
	v_pk_mul_f32 v[136:137], v[48:49], v[48:49]
	v_pk_mul_f32 v[128:129], v[50:51], v[50:51]
	v_pk_fma_f32 v[136:137], v[52:53], v[52:53], v[136:137]
	v_pk_fma_f32 v[128:129], v[54:55], v[54:55], v[128:129]
	v_pk_fma_f32 v[136:137], v[56:57], v[56:57], v[136:137]
	v_pk_fma_f32 v[128:129], v[58:59], v[58:59], v[128:129]
	v_pk_fma_f32 v[136:137], v[60:61], v[60:61], v[136:137]
	v_pk_fma_f32 v[128:129], v[62:63], v[62:63], v[128:129]
	v_pk_add_f32 v[136:137], v[136:137], v[128:129]
	s_nop 0
	v_add_f32_e32 v136, v136, v137
	s_nop 1
	v_add_f32_dpp v136, v136, v136 quad_perm:[1,0,3,2] row_mask:0xf bank_mask:0xf
	s_nop 1
	v_add_f32_dpp v136, v136, v136 quad_perm:[2,3,0,1] row_mask:0xf bank_mask:0xf
	s_nop 1
	v_add_f32_dpp v136, v136, v136 row_half_mirror row_mask:0xf bank_mask:0xf
	s_nop 1
	v_add_f32_dpp v136, v136, v136 row_mirror row_mask:0xf bank_mask:0xf
	s_nop 1
	v_add_f32_dpp v136, v136, v136 row_bcast:15 row_mask:0xa bank_mask:0xf
	s_nop 1
	v_add_f32_dpp v136, v136, v136 row_bcast:31 row_mask:0xc bank_mask:0xf
	s_nop 1
	v_readlane_b32 s16, v136, 63
	s_nop 3
	v_fma_f32 v138, s16, v140, v141
	v_rsq_f32_e32 v138, v138
	s_nop 0
	v_mov_b32_e32 v139, v138
	v_pk_mul_f32 v[48:49], v[48:49], v[138:139]
	v_pk_mul_f32 v[50:51], v[50:51], v[138:139]
	v_pk_mul_f32 v[52:53], v[52:53], v[138:139]
	v_pk_mul_f32 v[54:55], v[54:55], v[138:139]
	v_pk_mul_f32 v[56:57], v[56:57], v[138:139]
	v_pk_mul_f32 v[58:59], v[58:59], v[138:139]
	v_pk_mul_f32 v[60:61], v[60:61], v[138:139]
	v_pk_mul_f32 v[62:63], v[62:63], v[138:139]
	v_pk_mul_f32 v[48:49], v[48:49], v[112:113]
	v_pk_mul_f32 v[50:51], v[50:51], v[114:115]
	v_pk_mul_f32 v[52:53], v[52:53], v[116:117]
	v_pk_mul_f32 v[54:55], v[54:55], v[118:119]
	v_pk_mul_f32 v[56:57], v[56:57], v[120:121]
	v_pk_mul_f32 v[58:59], v[58:59], v[122:123]
	v_pk_mul_f32 v[60:61], v[60:61], v[124:125]
	v_pk_mul_f32 v[62:63], v[62:63], v[126:127]
	global_store_dwordx4 v142, v[48:51], s[8:9] nt
	global_store_dwordx4 v142, v[52:55], s[8:9] offset:1024 nt
	global_store_dwordx4 v142, v[56:59], s[8:9] offset:2048 nt
	global_store_dwordx4 v142, v[60:63], s[8:9] offset:3072 nt
	s_add_u32 s8, s8, s10
	s_addc_u32 s9, s9, 0
	s_cmp_ge_u32 s14, 0x8000
	s_cbranch_scc1 .Lfnorm_drain2
	global_load_dwordx4 v[48:51], v142, s[0:1] nt
	global_load_dwordx4 v[52:55], v142, s[0:1] offset:1024 nt
	global_load_dwordx4 v[56:59], v142, s[0:1] offset:2048 nt
	global_load_dwordx4 v[60:63], v142, s[0:1] offset:3072 nt
	global_load_dwordx2 v[64:65], v143, s[2:3] nt
	global_load_dwordx2 v[66:67], v143, s[2:3] offset:512 nt
	global_load_dwordx2 v[68:69], v143, s[2:3] offset:1024 nt
	global_load_dwordx2 v[70:71], v143, s[2:3] offset:1536 nt
	global_load_dwordx2 v[72:73], v143, s[6:7]
	global_load_dwordx2 v[74:75], v143, s[6:7] offset:512
	global_load_dwordx2 v[76:77], v143, s[6:7] offset:1024
	global_load_dwordx2 v[78:79], v143, s[6:7] offset:1536
	s_add_u32 s0, s0, s10
	s_addc_u32 s1, s1, 0
	s_add_u32 s2, s2, s12
	s_addc_u32 s3, s3, 0
	s_add_u32 s6, s6, s12
	s_addc_u32 s7, s7, 0
	s_add_u32 s14, s14, s15
	s_waitcnt vmcnt(24)
	v_lshlrev_b32_e32 v128, 16, v96
	v_and_b32_e32 v129, 0xffff0000, v96
	v_lshlrev_b32_e32 v130, 16, v97
	v_and_b32_e32 v131, 0xffff0000, v97
	v_pk_add_f32 v[80:81], v[80:81], v[128:129]
	v_pk_add_f32 v[82:83], v[82:83], v[130:131]
	v_lshlrev_b32_e32 v132, 16, v98
	v_and_b32_e32 v133, 0xffff0000, v98
	v_lshlrev_b32_e32 v134, 16, v99
	v_and_b32_e32 v135, 0xffff0000, v99
	v_pk_add_f32 v[84:85], v[84:85], v[132:133]
	v_pk_add_f32 v[86:87], v[86:87], v[134:135]
	v_lshlrev_b32_e32 v128, 16, v100
	v_and_b32_e32 v129, 0xffff0000, v100
	v_lshlrev_b32_e32 v130, 16, v101
	v_and_b32_e32 v131, 0xffff0000, v101
	v_pk_add_f32 v[88:89], v[88:89], v[128:129]
	v_pk_add_f32 v[90:91], v[90:91], v[130:131]
	v_lshlrev_b32_e32 v132, 16, v102
	v_and_b32_e32 v133, 0xffff0000, v102
	v_lshlrev_b32_e32 v134, 16, v103
	v_and_b32_e32 v135, 0xffff0000, v103
	v_pk_add_f32 v[92:93], v[92:93], v[132:133]
	v_pk_add_f32 v[94:95], v[94:95], v[134:135]
	v_lshlrev_b32_e32 v128, 16, v104
	v_and_b32_e32 v129, 0xffff0000, v104
	v_lshlrev_b32_e32 v130, 16, v105
	v_and_b32_e32 v131, 0xffff0000, v105
	v_pk_add_f32 v[80:81], v[80:81], v[128:129]
	v_pk_add_f32 v[82:83], v[82:83], v[130:131]
	v_lshlrev_b32_e32 v132, 16, v106
	v_and_b32_e32 v133, 0xffff0000, v106
	v_lshlrev_b32_e32 v134, 16, v107
	v_and_b32_e32 v135, 0xffff0000, v107
	v_pk_add_f32 v[84:85], v[84:85], v[132:133]
	v_pk_add_f32 v[86:87], v[86:87], v[134:135]
	v_lshlrev_b32_e32 v128, 16, v108
	v_and_b32_e32 v129, 0xffff0000, v108
	v_lshlrev_b32_e32 v130, 16, v109
	v_and_b32_e32 v131, 0xffff0000, v109
	v_pk_add_f32 v[88:89], v[88:89], v[128:129]
	v_pk_add_f32 v[90:91], v[90:91], v[130:131]
	v_lshlrev_b32_e32 v132, 16, v110
	v_and_b32_e32 v133, 0xffff0000, v110
	v_lshlrev_b32_e32 v134, 16, v111
	v_and_b32_e32 v135, 0xffff0000, v111
	v_pk_add_f32 v[92:93], v[92:93], v[132:133]
	v_pk_add_f32 v[94:95], v[94:95], v[134:135]
	v_pk_mul_f32 v[136:137], v[80:81], v[80:81]
	v_pk_mul_f32 v[128:129], v[82:83], v[82:83]
	v_pk_fma_f32 v[136:137], v[84:85], v[84:85], v[136:137]
	v_pk_fma_f32 v[128:129], v[86:87], v[86:87], v[128:129]
	v_pk_fma_f32 v[136:137], v[88:89], v[88:89], v[136:137]
	v_pk_fma_f32 v[128:129], v[90:91], v[90:91], v[128:129]
	v_pk_fma_f32 v[136:137], v[92:93], v[92:93], v[136:137]
	v_pk_fma_f32 v[128:129], v[94:95], v[94:95], v[128:129]
	v_pk_add_f32 v[136:137], v[136:137], v[128:129]
	s_nop 0
	v_add_f32_e32 v136, v136, v137
	s_nop 1
	v_add_f32_dpp v136, v136, v136 quad_perm:[1,0,3,2] row_mask:0xf bank_mask:0xf
	s_nop 1
	v_add_f32_dpp v136, v136, v136 quad_perm:[2,3,0,1] row_mask:0xf bank_mask:0xf
	s_nop 1
	v_add_f32_dpp v136, v136, v136 row_half_mirror row_mask:0xf bank_mask:0xf
	s_nop 1
	v_add_f32_dpp v136, v136, v136 row_mirror row_mask:0xf bank_mask:0xf
	s_nop 1
	v_add_f32_dpp v136, v136, v136 row_bcast:15 row_mask:0xa bank_mask:0xf
	s_nop 1
	v_add_f32_dpp v136, v136, v136 row_bcast:31 row_mask:0xc bank_mask:0xf
	s_nop 1
	v_readlane_b32 s16, v136, 63
	s_nop 3
	v_fma_f32 v138, s16, v140, v141
	v_rsq_f32_e32 v138, v138
	s_nop 0
	v_mov_b32_e32 v139, v138
	v_pk_mul_f32 v[80:81], v[80:81], v[138:139]
	v_pk_mul_f32 v[82:83], v[82:83], v[138:139]
	v_pk_mul_f32 v[84:85], v[84:85], v[138:139]
	v_pk_mul_f32 v[86:87], v[86:87], v[138:139]
	v_pk_mul_f32 v[88:89], v[88:89], v[138:139]
	v_pk_mul_f32 v[90:91], v[90:91], v[138:139]
	v_pk_mul_f32 v[92:93], v[92:93], v[138:139]
	v_pk_mul_f32 v[94:95], v[94:95], v[138:139]
	v_pk_mul_f32 v[80:81], v[80:81], v[112:113]
	v_pk_mul_f32 v[82:83], v[82:83], v[114:115]
	v_pk_mul_f32 v[84:85], v[84:85], v[116:117]
	v_pk_mul_f32 v[86:87], v[86:87], v[118:119]
	v_pk_mul_f32 v[88:89], v[88:89], v[120:121]
	v_pk_mul_f32 v[90:91], v[90:91], v[122:123]
	v_pk_mul_f32 v[92:93], v[92:93], v[124:125]
	v_pk_mul_f32 v[94:95], v[94:95], v[126:127]
	global_store_dwordx4 v142, v[80:83], s[8:9] nt
	global_store_dwordx4 v142, v[84:87], s[8:9] offset:1024 nt
	global_store_dwordx4 v142, v[88:91], s[8:9] offset:2048 nt
	global_store_dwordx4 v142, v[92:95], s[8:9] offset:3072 nt
	s_add_u32 s8, s8, s10
	s_addc_u32 s9, s9, 0
	s_branch .Lfnorm_loop
.Lfnorm_drain0:
	s_waitcnt vmcnt(12)
	v_lshlrev_b32_e32 v128, 16, v32
	v_and_b32_e32 v129, 0xffff0000, v32
	v_lshlrev_b32_e32 v130, 16, v33
	v_and_b32_e32 v131, 0xffff0000, v33
	v_pk_add_f32 v[16:17], v[16:17], v[128:129]
	v_pk_add_f32 v[18:19], v[18:19], v[130:131]
	v_lshlrev_b32_e32 v132, 16, v34
	v_and_b32_e32 v133, 0xffff0000, v34
	v_lshlrev_b32_e32 v134, 16, v35
	v_and_b32_e32 v135, 0xffff0000, v35
	v_pk_add_f32 v[20:21], v[20:21], v[132:133]
	v_pk_add_f32 v[22:23], v[22:23], v[134:135]
	v_lshlrev_b32_e32 v128, 16, v36
	v_and_b32_e32 v129, 0xffff0000, v36
	v_lshlrev_b32_e32 v130, 16, v37
	v_and_b32_e32 v131, 0xffff0000, v37
	v_pk_add_f32 v[24:25], v[24:25], v[128:129]
	v_pk_add_f32 v[26:27], v[26:27], v[130:131]
	v_lshlrev_b32_e32 v132, 16, v38
	v_and_b32_e32 v133, 0xffff0000, v38
	v_lshlrev_b32_e32 v134, 16, v39
	v_and_b32_e32 v135, 0xffff0000, v39
	v_pk_add_f32 v[28:29], v[28:29], v[132:133]
	v_pk_add_f32 v[30:31], v[30:31], v[134:135]
	v_lshlrev_b32_e32 v128, 16, v40
	v_and_b32_e32 v129, 0xffff0000, v40
	v_lshlrev_b32_e32 v130, 16, v41
	v_and_b32_e32 v131, 0xffff0000, v41
	v_pk_add_f32 v[16:17], v[16:17], v[128:129]
	v_pk_add_f32 v[18:19], v[18:19], v[130:131]
	v_lshlrev_b32_e32 v132, 16, v42
	v_and_b32_e32 v133, 0xffff0000, v42
	v_lshlrev_b32_e32 v134, 16, v43
	v_and_b32_e32 v135, 0xffff0000, v43
	v_pk_add_f32 v[20:21], v[20:21], v[132:133]
	v_pk_add_f32 v[22:23], v[22:23], v[134:135]
	v_lshlrev_b32_e32 v128, 16, v44
	v_and_b32_e32 v129, 0xffff0000, v44
	v_lshlrev_b32_e32 v130, 16, v45
	v_and_b32_e32 v131, 0xffff0000, v45
	v_pk_add_f32 v[24:25], v[24:25], v[128:129]
	v_pk_add_f32 v[26:27], v[26:27], v[130:131]
	v_lshlrev_b32_e32 v132, 16, v46
	v_and_b32_e32 v133, 0xffff0000, v46
	v_lshlrev_b32_e32 v134, 16, v47
	v_and_b32_e32 v135, 0xffff0000, v47
	v_pk_add_f32 v[28:29], v[28:29], v[132:133]
	v_pk_add_f32 v[30:31], v[30:31], v[134:135]
	v_pk_mul_f32 v[136:137], v[16:17], v[16:17]
	v_pk_mul_f32 v[128:129], v[18:19], v[18:19]
	v_pk_fma_f32 v[136:137], v[20:21], v[20:21], v[136:137]
	v_pk_fma_f32 v[128:129], v[22:23], v[22:23], v[128:129]
	v_pk_fma_f32 v[136:137], v[24:25], v[24:25], v[136:137]
	v_pk_fma_f32 v[128:129], v[26:27], v[26:27], v[128:129]
	v_pk_fma_f32 v[136:137], v[28:29], v[28:29], v[136:137]
	v_pk_fma_f32 v[128:129], v[30:31], v[30:31], v[128:129]
	v_pk_add_f32 v[136:137], v[136:137], v[128:129]
	s_nop 0
	v_add_f32_e32 v136, v136, v137
	s_nop 1
	v_add_f32_dpp v136, v136, v136 quad_perm:[1,0,3,2] row_mask:0xf bank_mask:0xf
	s_nop 1
	v_add_f32_dpp v136, v136, v136 quad_perm:[2,3,0,1] row_mask:0xf bank_mask:0xf
	s_nop 1
	v_add_f32_dpp v136, v136, v136 row_half_mirror row_mask:0xf bank_mask:0xf
	s_nop 1
	v_add_f32_dpp v136, v136, v136 row_mirror row_mask:0xf bank_mask:0xf
	s_nop 1
	v_add_f32_dpp v136, v136, v136 row_bcast:15 row_mask:0xa bank_mask:0xf
	s_nop 1
	v_add_f32_dpp v136, v136, v136 row_bcast:31 row_mask:0xc bank_mask:0xf
	s_nop 1
	v_readlane_b32 s16, v136, 63
	s_nop 3
	v_fma_f32 v138, s16, v140, v141
	v_rsq_f32_e32 v138, v138
	s_nop 0
	v_mov_b32_e32 v139, v138
	v_pk_mul_f32 v[16:17], v[16:17], v[138:139]
	v_pk_mul_f32 v[18:19], v[18:19], v[138:139]
	v_pk_mul_f32 v[20:21], v[20:21], v[138:139]
	v_pk_mul_f32 v[22:23], v[22:23], v[138:139]
	v_pk_mul_f32 v[24:25], v[24:25], v[138:139]
	v_pk_mul_f32 v[26:27], v[26:27], v[138:139]
	v_pk_mul_f32 v[28:29], v[28:29], v[138:139]
	v_pk_mul_f32 v[30:31], v[30:31], v[138:139]
	v_pk_mul_f32 v[16:17], v[16:17], v[112:113]
	v_pk_mul_f32 v[18:19], v[18:19], v[114:115]
	v_pk_mul_f32 v[20:21], v[20:21], v[116:117]
	v_pk_mul_f32 v[22:23], v[22:23], v[118:119]
	v_pk_mul_f32 v[24:25], v[24:25], v[120:121]
	v_pk_mul_f32 v[26:27], v[26:27], v[122:123]
	v_pk_mul_f32 v[28:29], v[28:29], v[124:125]
	v_pk_mul_f32 v[30:31], v[30:31], v[126:127]
	global_store_dwordx4 v142, v[16:19], s[8:9] nt
	global_store_dwordx4 v142, v[20:23], s[8:9] offset:1024 nt
	global_store_dwordx4 v142, v[24:27], s[8:9] offset:2048 nt
	global_store_dwordx4 v142, v[28:31], s[8:9] offset:3072 nt
	s_add_u32 s8, s8, s10
	s_addc_u32 s9, s9, 0
	s_waitcnt vmcnt(4)
	v_lshlrev_b32_e32 v128, 16, v64
	v_and_b32_e32 v129, 0xffff0000, v64
	v_lshlrev_b32_e32 v130, 16, v65
	v_and_b32_e32 v131, 0xffff0000, v65
	v_pk_add_f32 v[48:49], v[48:49], v[128:129]
	v_pk_add_f32 v[50:51], v[50:51], v[130:131]
	v_lshlrev_b32_e32 v132, 16, v66
	v_and_b32_e32 v133, 0xffff0000, v66
	v_lshlrev_b32_e32 v134, 16, v67
	v_and_b32_e32 v135, 0xffff0000, v67
	v_pk_add_f32 v[52:53], v[52:53], v[132:133]
	v_pk_add_f32 v[54:55], v[54:55], v[134:135]
	v_lshlrev_b32_e32 v128, 16, v68
	v_and_b32_e32 v129, 0xffff0000, v68
	v_lshlrev_b32_e32 v130, 16, v69
	v_and_b32_e32 v131, 0xffff0000, v69
	v_pk_add_f32 v[56:57], v[56:57], v[128:129]
	v_pk_add_f32 v[58:59], v[58:59], v[130:131]
	v_lshlrev_b32_e32 v132, 16, v70
	v_and_b32_e32 v133, 0xffff0000, v70
	v_lshlrev_b32_e32 v134, 16, v71
	v_and_b32_e32 v135, 0xffff0000, v71
	v_pk_add_f32 v[60:61], v[60:61], v[132:133]
	v_pk_add_f32 v[62:63], v[62:63], v[134:135]
	v_lshlrev_b32_e32 v128, 16, v72
	v_and_b32_e32 v129, 0xffff0000, v72
	v_lshlrev_b32_e32 v130, 16, v73
	v_and_b32_e32 v131, 0xffff0000, v73
	v_pk_add_f32 v[48:49], v[48:49], v[128:129]
	v_pk_add_f32 v[50:51], v[50:51], v[130:131]
	v_lshlrev_b32_e32 v132, 16, v74
	v_and_b32_e32 v133, 0xffff0000, v74
	v_lshlrev_b32_e32 v134, 16, v75
	v_and_b32_e32 v135, 0xffff0000, v75
	v_pk_add_f32 v[52:53], v[52:53], v[132:133]
	v_pk_add_f32 v[54:55], v[54:55], v[134:135]
	v_lshlrev_b32_e32 v128, 16, v76
	v_and_b32_e32 v129, 0xffff0000, v76
	v_lshlrev_b32_e32 v130, 16, v77
	v_and_b32_e32 v131, 0xffff0000, v77
	v_pk_add_f32 v[56:57], v[56:57], v[128:129]
	v_pk_add_f32 v[58:59], v[58:59], v[130:131]
	v_lshlrev_b32_e32 v132, 16, v78
	v_and_b32_e32 v133, 0xffff0000, v78
	v_lshlrev_b32_e32 v134, 16, v79
	v_and_b32_e32 v135, 0xffff0000, v79
	v_pk_add_f32 v[60:61], v[60:61], v[132:133]
	v_pk_add_f32 v[62:63], v[62:63], v[134:135]
	v_pk_mul_f32 v[136:137], v[48:49], v[48:49]
	v_pk_mul_f32 v[128:129], v[50:51], v[50:51]
	v_pk_fma_f32 v[136:137], v[52:53], v[52:53], v[136:137]
	v_pk_fma_f32 v[128:129], v[54:55], v[54:55], v[128:129]
	v_pk_fma_f32 v[136:137], v[56:57], v[56:57], v[136:137]
	v_pk_fma_f32 v[128:129], v[58:59], v[58:59], v[128:129]
	v_pk_fma_f32 v[136:137], v[60:61], v[60:61], v[136:137]
	v_pk_fma_f32 v[128:129], v[62:63], v[62:63], v[128:129]
	v_pk_add_f32 v[136:137], v[136:137], v[128:129]
	s_nop 0
	v_add_f32_e32 v136, v136, v137
	s_nop 1
	v_add_f32_dpp v136, v136, v136 quad_perm:[1,0,3,2] row_mask:0xf bank_mask:0xf
	s_nop 1
	v_add_f32_dpp v136, v136, v136 quad_perm:[2,3,0,1] row_mask:0xf bank_mask:0xf
	s_nop 1
	v_add_f32_dpp v136, v136, v136 row_half_mirror row_mask:0xf bank_mask:0xf
	s_nop 1
	v_add_f32_dpp v136, v136, v136 row_mirror row_mask:0xf bank_mask:0xf
	s_nop 1
	v_add_f32_dpp v136, v136, v136 row_bcast:15 row_mask:0xa bank_mask:0xf
	s_nop 1
	v_add_f32_dpp v136, v136, v136 row_bcast:31 row_mask:0xc bank_mask:0xf
	s_nop 1
	v_readlane_b32 s16, v136, 63
	s_nop 3
	v_fma_f32 v138, s16, v140, v141
	v_rsq_f32_e32 v138, v138
	s_nop 0
	v_mov_b32_e32 v139, v138
	v_pk_mul_f32 v[48:49], v[48:49], v[138:139]
	v_pk_mul_f32 v[50:51], v[50:51], v[138:139]
	v_pk_mul_f32 v[52:53], v[52:53], v[138:139]
	v_pk_mul_f32 v[54:55], v[54:55], v[138:139]
	v_pk_mul_f32 v[56:57], v[56:57], v[138:139]
	v_pk_mul_f32 v[58:59], v[58:59], v[138:139]
	v_pk_mul_f32 v[60:61], v[60:61], v[138:139]
	v_pk_mul_f32 v[62:63], v[62:63], v[138:139]
	v_pk_mul_f32 v[48:49], v[48:49], v[112:113]
	v_pk_mul_f32 v[50:51], v[50:51], v[114:115]
	v_pk_mul_f32 v[52:53], v[52:53], v[116:117]
	v_pk_mul_f32 v[54:55], v[54:55], v[118:119]
	v_pk_mul_f32 v[56:57], v[56:57], v[120:121]
	v_pk_mul_f32 v[58:59], v[58:59], v[122:123]
	v_pk_mul_f32 v[60:61], v[60:61], v[124:125]
	v_pk_mul_f32 v[62:63], v[62:63], v[126:127]
	global_store_dwordx4 v142, v[48:51], s[8:9] nt
	global_store_dwordx4 v142, v[52:55], s[8:9] offset:1024 nt
	global_store_dwordx4 v142, v[56:59], s[8:9] offset:2048 nt
	global_store_dwordx4 v142, v[60:63], s[8:9] offset:3072 nt
	s_add_u32 s8, s8, s10
	s_addc_u32 s9, s9, 0
	s_branch .Lfnorm_done
.Lfnorm_drain1:
	s_waitcnt vmcnt(12)
	v_lshlrev_b32_e32 v128, 16, v64
	v_and_b32_e32 v129, 0xffff0000, v64
	v_lshlrev_b32_e32 v130, 16, v65
	v_and_b32_e32 v131, 0xffff0000, v65
	v_pk_add_f32 v[48:49], v[48:49], v[128:129]
	v_pk_add_f32 v[50:51], v[50:51], v[130:131]
	v_lshlrev_b32_e32 v132, 16, v66
	v_and_b32_e32 v133, 0xffff0000, v66
	v_lshlrev_b32_e32 v134, 16, v67
	v_and_b32_e32 v135, 0xffff0000, v67
	v_pk_add_f32 v[52:53], v[52:53], v[132:133]
	v_pk_add_f32 v[54:55], v[54:55], v[134:135]
	v_lshlrev_b32_e32 v128, 16, v68
	v_and_b32_e32 v129, 0xffff0000, v68
	v_lshlrev_b32_e32 v130, 16, v69
	v_and_b32_e32 v131, 0xffff0000, v69
	v_pk_add_f32 v[56:57], v[56:57], v[128:129]
	v_pk_add_f32 v[58:59], v[58:59], v[130:131]
	v_lshlrev_b32_e32 v132, 16, v70
	v_and_b32_e32 v133, 0xffff0000, v70
	v_lshlrev_b32_e32 v134, 16, v71
	v_and_b32_e32 v135, 0xffff0000, v71
	v_pk_add_f32 v[60:61], v[60:61], v[132:133]
	v_pk_add_f32 v[62:63], v[62:63], v[134:135]
	v_lshlrev_b32_e32 v128, 16, v72
	v_and_b32_e32 v129, 0xffff0000, v72
	v_lshlrev_b32_e32 v130, 16, v73
	v_and_b32_e32 v131, 0xffff0000, v73
	v_pk_add_f32 v[48:49], v[48:49], v[128:129]
	v_pk_add_f32 v[50:51], v[50:51], v[130:131]
	v_lshlrev_b32_e32 v132, 16, v74
	v_and_b32_e32 v133, 0xffff0000, v74
	v_lshlrev_b32_e32 v134, 16, v75
	v_and_b32_e32 v135, 0xffff0000, v75
	v_pk_add_f32 v[52:53], v[52:53], v[132:133]
	v_pk_add_f32 v[54:55], v[54:55], v[134:135]
	v_lshlrev_b32_e32 v128, 16, v76
	v_and_b32_e32 v129, 0xffff0000, v76
	v_lshlrev_b32_e32 v130, 16, v77
	v_and_b32_e32 v131, 0xffff0000, v77
	v_pk_add_f32 v[56:57], v[56:57], v[128:129]
	v_pk_add_f32 v[58:59], v[58:59], v[130:131]
	v_lshlrev_b32_e32 v132, 16, v78
	v_and_b32_e32 v133, 0xffff0000, v78
	v_lshlrev_b32_e32 v134, 16, v79
	v_and_b32_e32 v135, 0xffff0000, v79
	v_pk_add_f32 v[60:61], v[60:61], v[132:133]
	v_pk_add_f32 v[62:63], v[62:63], v[134:135]
	v_pk_mul_f32 v[136:137], v[48:49], v[48:49]
	v_pk_mul_f32 v[128:129], v[50:51], v[50:51]
	v_pk_fma_f32 v[136:137], v[52:53], v[52:53], v[136:137]
	v_pk_fma_f32 v[128:129], v[54:55], v[54:55], v[128:129]
	v_pk_fma_f32 v[136:137], v[56:57], v[56:57], v[136:137]
	v_pk_fma_f32 v[128:129], v[58:59], v[58:59], v[128:129]
	v_pk_fma_f32 v[136:137], v[60:61], v[60:61], v[136:137]
	v_pk_fma_f32 v[128:129], v[62:63], v[62:63], v[128:129]
	v_pk_add_f32 v[136:137], v[136:137], v[128:129]
	s_nop 0
	v_add_f32_e32 v136, v136, v137
	s_nop 1
	v_add_f32_dpp v136, v136, v136 quad_perm:[1,0,3,2] row_mask:0xf bank_mask:0xf
	s_nop 1
	v_add_f32_dpp v136, v136, v136 quad_perm:[2,3,0,1] row_mask:0xf bank_mask:0xf
	s_nop 1
	v_add_f32_dpp v136, v136, v136 row_half_mirror row_mask:0xf bank_mask:0xf
	s_nop 1
	v_add_f32_dpp v136, v136, v136 row_mirror row_mask:0xf bank_mask:0xf
	s_nop 1
	v_add_f32_dpp v136, v136, v136 row_bcast:15 row_mask:0xa bank_mask:0xf
	s_nop 1
	v_add_f32_dpp v136, v136, v136 row_bcast:31 row_mask:0xc bank_mask:0xf
	s_nop 1
	v_readlane_b32 s16, v136, 63
	s_nop 3
	v_fma_f32 v138, s16, v140, v141
	v_rsq_f32_e32 v138, v138
	s_nop 0
	v_mov_b32_e32 v139, v138
	v_pk_mul_f32 v[48:49], v[48:49], v[138:139]
	v_pk_mul_f32 v[50:51], v[50:51], v[138:139]
	v_pk_mul_f32 v[52:53], v[52:53], v[138:139]
	v_pk_mul_f32 v[54:55], v[54:55], v[138:139]
	v_pk_mul_f32 v[56:57], v[56:57], v[138:139]
	v_pk_mul_f32 v[58:59], v[58:59], v[138:139]
	v_pk_mul_f32 v[60:61], v[60:61], v[138:139]
	v_pk_mul_f32 v[62:63], v[62:63], v[138:139]
	v_pk_mul_f32 v[48:49], v[48:49], v[112:113]
	v_pk_mul_f32 v[50:51], v[50:51], v[114:115]
	v_pk_mul_f32 v[52:53], v[52:53], v[116:117]
	v_pk_mul_f32 v[54:55], v[54:55], v[118:119]
	v_pk_mul_f32 v[56:57], v[56:57], v[120:121]
	v_pk_mul_f32 v[58:59], v[58:59], v[122:123]
	v_pk_mul_f32 v[60:61], v[60:61], v[124:125]
	v_pk_mul_f32 v[62:63], v[62:63], v[126:127]
	global_store_dwordx4 v142, v[48:51], s[8:9] nt
	global_store_dwordx4 v142, v[52:55], s[8:9] offset:1024 nt
	global_store_dwordx4 v142, v[56:59], s[8:9] offset:2048 nt
	global_store_dwordx4 v142, v[60:63], s[8:9] offset:3072 nt
	s_add_u32 s8, s8, s10
	s_addc_u32 s9, s9, 0
	s_waitcnt vmcnt(4)
	v_lshlrev_b32_e32 v128, 16, v96
	v_and_b32_e32 v129, 0xffff0000, v96
	v_lshlrev_b32_e32 v130, 16, v97
	v_and_b32_e32 v131, 0xffff0000, v97
	v_pk_add_f32 v[80:81], v[80:81], v[128:129]
	v_pk_add_f32 v[82:83], v[82:83], v[130:131]
	v_lshlrev_b32_e32 v132, 16, v98
	v_and_b32_e32 v133, 0xffff0000, v98
	v_lshlrev_b32_e32 v134, 16, v99
	v_and_b32_e32 v135, 0xffff0000, v99
	v_pk_add_f32 v[84:85], v[84:85], v[132:133]
	v_pk_add_f32 v[86:87], v[86:87], v[134:135]
	v_lshlrev_b32_e32 v128, 16, v100
	v_and_b32_e32 v129, 0xffff0000, v100
	v_lshlrev_b32_e32 v130, 16, v101
	v_and_b32_e32 v131, 0xffff0000, v101
	v_pk_add_f32 v[88:89], v[88:89], v[128:129]
	v_pk_add_f32 v[90:91], v[90:91], v[130:131]
	v_lshlrev_b32_e32 v132, 16, v102
	v_and_b32_e32 v133, 0xffff0000, v102
	v_lshlrev_b32_e32 v134, 16, v103
	v_and_b32_e32 v135, 0xffff0000, v103
	v_pk_add_f32 v[92:93], v[92:93], v[132:133]
	v_pk_add_f32 v[94:95], v[94:95], v[134:135]
	v_lshlrev_b32_e32 v128, 16, v104
	v_and_b32_e32 v129, 0xffff0000, v104
	v_lshlrev_b32_e32 v130, 16, v105
	v_and_b32_e32 v131, 0xffff0000, v105
	v_pk_add_f32 v[80:81], v[80:81], v[128:129]
	v_pk_add_f32 v[82:83], v[82:83], v[130:131]
	v_lshlrev_b32_e32 v132, 16, v106
	v_and_b32_e32 v133, 0xffff0000, v106
	v_lshlrev_b32_e32 v134, 16, v107
	v_and_b32_e32 v135, 0xffff0000, v107
	v_pk_add_f32 v[84:85], v[84:85], v[132:133]
	v_pk_add_f32 v[86:87], v[86:87], v[134:135]
	v_lshlrev_b32_e32 v128, 16, v108
	v_and_b32_e32 v129, 0xffff0000, v108
	v_lshlrev_b32_e32 v130, 16, v109
	v_and_b32_e32 v131, 0xffff0000, v109
	v_pk_add_f32 v[88:89], v[88:89], v[128:129]
	v_pk_add_f32 v[90:91], v[90:91], v[130:131]
	v_lshlrev_b32_e32 v132, 16, v110
	v_and_b32_e32 v133, 0xffff0000, v110
	v_lshlrev_b32_e32 v134, 16, v111
	v_and_b32_e32 v135, 0xffff0000, v111
	v_pk_add_f32 v[92:93], v[92:93], v[132:133]
	v_pk_add_f32 v[94:95], v[94:95], v[134:135]
	v_pk_mul_f32 v[136:137], v[80:81], v[80:81]
	v_pk_mul_f32 v[128:129], v[82:83], v[82:83]
	v_pk_fma_f32 v[136:137], v[84:85], v[84:85], v[136:137]
	v_pk_fma_f32 v[128:129], v[86:87], v[86:87], v[128:129]
	v_pk_fma_f32 v[136:137], v[88:89], v[88:89], v[136:137]
	v_pk_fma_f32 v[128:129], v[90:91], v[90:91], v[128:129]
	v_pk_fma_f32 v[136:137], v[92:93], v[92:93], v[136:137]
	v_pk_fma_f32 v[128:129], v[94:95], v[94:95], v[128:129]
	v_pk_add_f32 v[136:137], v[136:137], v[128:129]
	s_nop 0
	v_add_f32_e32 v136, v136, v137
	s_nop 1
	v_add_f32_dpp v136, v136, v136 quad_perm:[1,0,3,2] row_mask:0xf bank_mask:0xf
	s_nop 1
	v_add_f32_dpp v136, v136, v136 quad_perm:[2,3,0,1] row_mask:0xf bank_mask:0xf
	s_nop 1
	v_add_f32_dpp v136, v136, v136 row_half_mirror row_mask:0xf bank_mask:0xf
	s_nop 1
	v_add_f32_dpp v136, v136, v136 row_mirror row_mask:0xf bank_mask:0xf
	s_nop 1
	v_add_f32_dpp v136, v136, v136 row_bcast:15 row_mask:0xa bank_mask:0xf
	s_nop 1
	v_add_f32_dpp v136, v136, v136 row_bcast:31 row_mask:0xc bank_mask:0xf
	s_nop 1
	v_readlane_b32 s16, v136, 63
	s_nop 3
	v_fma_f32 v138, s16, v140, v141
	v_rsq_f32_e32 v138, v138
	s_nop 0
	v_mov_b32_e32 v139, v138
	v_pk_mul_f32 v[80:81], v[80:81], v[138:139]
	v_pk_mul_f32 v[82:83], v[82:83], v[138:139]
	v_pk_mul_f32 v[84:85], v[84:85], v[138:139]
	v_pk_mul_f32 v[86:87], v[86:87], v[138:139]
	v_pk_mul_f32 v[88:89], v[88:89], v[138:139]
	v_pk_mul_f32 v[90:91], v[90:91], v[138:139]
	v_pk_mul_f32 v[92:93], v[92:93], v[138:139]
	v_pk_mul_f32 v[94:95], v[94:95], v[138:139]
	v_pk_mul_f32 v[80:81], v[80:81], v[112:113]
	v_pk_mul_f32 v[82:83], v[82:83], v[114:115]
	v_pk_mul_f32 v[84:85], v[84:85], v[116:117]
	v_pk_mul_f32 v[86:87], v[86:87], v[118:119]
	v_pk_mul_f32 v[88:89], v[88:89], v[120:121]
	v_pk_mul_f32 v[90:91], v[90:91], v[122:123]
	v_pk_mul_f32 v[92:93], v[92:93], v[124:125]
	v_pk_mul_f32 v[94:95], v[94:95], v[126:127]
	global_store_dwordx4 v142, v[80:83], s[8:9] nt
	global_store_dwordx4 v142, v[84:87], s[8:9] offset:1024 nt
	global_store_dwordx4 v142, v[88:91], s[8:9] offset:2048 nt
	global_store_dwordx4 v142, v[92:95], s[8:9] offset:3072 nt
	s_add_u32 s8, s8, s10
	s_addc_u32 s9, s9, 0
	s_branch .Lfnorm_done
.Lfnorm_drain2:
	s_waitcnt vmcnt(12)
	v_lshlrev_b32_e32 v128, 16, v96
	v_and_b32_e32 v129, 0xffff0000, v96
	v_lshlrev_b32_e32 v130, 16, v97
	v_and_b32_e32 v131, 0xffff0000, v97
	v_pk_add_f32 v[80:81], v[80:81], v[128:129]
	v_pk_add_f32 v[82:83], v[82:83], v[130:131]
	v_lshlrev_b32_e32 v132, 16, v98
	v_and_b32_e32 v133, 0xffff0000, v98
	v_lshlrev_b32_e32 v134, 16, v99
	v_and_b32_e32 v135, 0xffff0000, v99
	v_pk_add_f32 v[84:85], v[84:85], v[132:133]
	v_pk_add_f32 v[86:87], v[86:87], v[134:135]
	v_lshlrev_b32_e32 v128, 16, v100
	v_and_b32_e32 v129, 0xffff0000, v100
	v_lshlrev_b32_e32 v130, 16, v101
	v_and_b32_e32 v131, 0xffff0000, v101
	v_pk_add_f32 v[88:89], v[88:89], v[128:129]
	v_pk_add_f32 v[90:91], v[90:91], v[130:131]
	v_lshlrev_b32_e32 v132, 16, v102
	v_and_b32_e32 v133, 0xffff0000, v102
	v_lshlrev_b32_e32 v134, 16, v103
	v_and_b32_e32 v135, 0xffff0000, v103
	v_pk_add_f32 v[92:93], v[92:93], v[132:133]
	v_pk_add_f32 v[94:95], v[94:95], v[134:135]
	v_lshlrev_b32_e32 v128, 16, v104
	v_and_b32_e32 v129, 0xffff0000, v104
	v_lshlrev_b32_e32 v130, 16, v105
	v_and_b32_e32 v131, 0xffff0000, v105
	v_pk_add_f32 v[80:81], v[80:81], v[128:129]
	v_pk_add_f32 v[82:83], v[82:83], v[130:131]
	v_lshlrev_b32_e32 v132, 16, v106
	v_and_b32_e32 v133, 0xffff0000, v106
	v_lshlrev_b32_e32 v134, 16, v107
	v_and_b32_e32 v135, 0xffff0000, v107
	v_pk_add_f32 v[84:85], v[84:85], v[132:133]
	v_pk_add_f32 v[86:87], v[86:87], v[134:135]
	v_lshlrev_b32_e32 v128, 16, v108
	v_and_b32_e32 v129, 0xffff0000, v108
	v_lshlrev_b32_e32 v130, 16, v109
	v_and_b32_e32 v131, 0xffff0000, v109
	v_pk_add_f32 v[88:89], v[88:89], v[128:129]
	v_pk_add_f32 v[90:91], v[90:91], v[130:131]
	v_lshlrev_b32_e32 v132, 16, v110
	v_and_b32_e32 v133, 0xffff0000, v110
	v_lshlrev_b32_e32 v134, 16, v111
	v_and_b32_e32 v135, 0xffff0000, v111
	v_pk_add_f32 v[92:93], v[92:93], v[132:133]
	v_pk_add_f32 v[94:95], v[94:95], v[134:135]
	v_pk_mul_f32 v[136:137], v[80:81], v[80:81]
	v_pk_mul_f32 v[128:129], v[82:83], v[82:83]
	v_pk_fma_f32 v[136:137], v[84:85], v[84:85], v[136:137]
	v_pk_fma_f32 v[128:129], v[86:87], v[86:87], v[128:129]
	v_pk_fma_f32 v[136:137], v[88:89], v[88:89], v[136:137]
	v_pk_fma_f32 v[128:129], v[90:91], v[90:91], v[128:129]
	v_pk_fma_f32 v[136:137], v[92:93], v[92:93], v[136:137]
	v_pk_fma_f32 v[128:129], v[94:95], v[94:95], v[128:129]
	v_pk_add_f32 v[136:137], v[136:137], v[128:129]
	s_nop 0
	v_add_f32_e32 v136, v136, v137
	s_nop 1
	v_add_f32_dpp v136, v136, v136 quad_perm:[1,0,3,2] row_mask:0xf bank_mask:0xf
	s_nop 1
	v_add_f32_dpp v136, v136, v136 quad_perm:[2,3,0,1] row_mask:0xf bank_mask:0xf
	s_nop 1
	v_add_f32_dpp v136, v136, v136 row_half_mirror row_mask:0xf bank_mask:0xf
	s_nop 1
	v_add_f32_dpp v136, v136, v136 row_mirror row_mask:0xf bank_mask:0xf
	s_nop 1
	v_add_f32_dpp v136, v136, v136 row_bcast:15 row_mask:0xa bank_mask:0xf
	s_nop 1
	v_add_f32_dpp v136, v136, v136 row_bcast:31 row_mask:0xc bank_mask:0xf
	s_nop 1
	v_readlane_b32 s16, v136, 63
	s_nop 3
	v_fma_f32 v138, s16, v140, v141
	v_rsq_f32_e32 v138, v138
	s_nop 0
	v_mov_b32_e32 v139, v138
	v_pk_mul_f32 v[80:81], v[80:81], v[138:139]
	v_pk_mul_f32 v[82:83], v[82:83], v[138:139]
	v_pk_mul_f32 v[84:85], v[84:85], v[138:139]
	v_pk_mul_f32 v[86:87], v[86:87], v[138:139]
	v_pk_mul_f32 v[88:89], v[88:89], v[138:139]
	v_pk_mul_f32 v[90:91], v[90:91], v[138:139]
	v_pk_mul_f32 v[92:93], v[92:93], v[138:139]
	v_pk_mul_f32 v[94:95], v[94:95], v[138:139]
	v_pk_mul_f32 v[80:81], v[80:81], v[112:113]
	v_pk_mul_f32 v[82:83], v[82:83], v[114:115]
	v_pk_mul_f32 v[84:85], v[84:85], v[116:117]
	v_pk_mul_f32 v[86:87], v[86:87], v[118:119]
	v_pk_mul_f32 v[88:89], v[88:89], v[120:121]
	v_pk_mul_f32 v[90:91], v[90:91], v[122:123]
	v_pk_mul_f32 v[92:93], v[92:93], v[124:125]
	v_pk_mul_f32 v[94:95], v[94:95], v[126:127]
	global_store_dwordx4 v142, v[80:83], s[8:9] nt
	global_store_dwordx4 v142, v[84:87], s[8:9] offset:1024 nt
	global_store_dwordx4 v142, v[88:91], s[8:9] offset:2048 nt
	global_store_dwordx4 v142, v[92:95], s[8:9] offset:3072 nt
	s_add_u32 s8, s8, s10
	s_addc_u32 s9, s9, 0
	s_waitcnt vmcnt(4)
	v_lshlrev_b32_e32 v128, 16, v32
	v_and_b32_e32 v129, 0xffff0000, v32
	v_lshlrev_b32_e32 v130, 16, v33
	v_and_b32_e32 v131, 0xffff0000, v33
	v_pk_add_f32 v[16:17], v[16:17], v[128:129]
	v_pk_add_f32 v[18:19], v[18:19], v[130:131]
	v_lshlrev_b32_e32 v132, 16, v34
	v_and_b32_e32 v133, 0xffff0000, v34
	v_lshlrev_b32_e32 v134, 16, v35
	v_and_b32_e32 v135, 0xffff0000, v35
	v_pk_add_f32 v[20:21], v[20:21], v[132:133]
	v_pk_add_f32 v[22:23], v[22:23], v[134:135]
	v_lshlrev_b32_e32 v128, 16, v36
	v_and_b32_e32 v129, 0xffff0000, v36
	v_lshlrev_b32_e32 v130, 16, v37
	v_and_b32_e32 v131, 0xffff0000, v37
	v_pk_add_f32 v[24:25], v[24:25], v[128:129]
	v_pk_add_f32 v[26:27], v[26:27], v[130:131]
	v_lshlrev_b32_e32 v132, 16, v38
	v_and_b32_e32 v133, 0xffff0000, v38
	v_lshlrev_b32_e32 v134, 16, v39
	v_and_b32_e32 v135, 0xffff0000, v39
	v_pk_add_f32 v[28:29], v[28:29], v[132:133]
	v_pk_add_f32 v[30:31], v[30:31], v[134:135]
	v_lshlrev_b32_e32 v128, 16, v40
	v_and_b32_e32 v129, 0xffff0000, v40
	v_lshlrev_b32_e32 v130, 16, v41
	v_and_b32_e32 v131, 0xffff0000, v41
	v_pk_add_f32 v[16:17], v[16:17], v[128:129]
	v_pk_add_f32 v[18:19], v[18:19], v[130:131]
	v_lshlrev_b32_e32 v132, 16, v42
	v_and_b32_e32 v133, 0xffff0000, v42
	v_lshlrev_b32_e32 v134, 16, v43
	v_and_b32_e32 v135, 0xffff0000, v43
	v_pk_add_f32 v[20:21], v[20:21], v[132:133]
	v_pk_add_f32 v[22:23], v[22:23], v[134:135]
	v_lshlrev_b32_e32 v128, 16, v44
	v_and_b32_e32 v129, 0xffff0000, v44
	v_lshlrev_b32_e32 v130, 16, v45
	v_and_b32_e32 v131, 0xffff0000, v45
	v_pk_add_f32 v[24:25], v[24:25], v[128:129]
	v_pk_add_f32 v[26:27], v[26:27], v[130:131]
	v_lshlrev_b32_e32 v132, 16, v46
	v_and_b32_e32 v133, 0xffff0000, v46
	v_lshlrev_b32_e32 v134, 16, v47
	v_and_b32_e32 v135, 0xffff0000, v47
	v_pk_add_f32 v[28:29], v[28:29], v[132:133]
	v_pk_add_f32 v[30:31], v[30:31], v[134:135]
	v_pk_mul_f32 v[136:137], v[16:17], v[16:17]
	v_pk_mul_f32 v[128:129], v[18:19], v[18:19]
	v_pk_fma_f32 v[136:137], v[20:21], v[20:21], v[136:137]
	v_pk_fma_f32 v[128:129], v[22:23], v[22:23], v[128:129]
	v_pk_fma_f32 v[136:137], v[24:25], v[24:25], v[136:137]
	v_pk_fma_f32 v[128:129], v[26:27], v[26:27], v[128:129]
	v_pk_fma_f32 v[136:137], v[28:29], v[28:29], v[136:137]
	v_pk_fma_f32 v[128:129], v[30:31], v[30:31], v[128:129]
	v_pk_add_f32 v[136:137], v[136:137], v[128:129]
	s_nop 0
	v_add_f32_e32 v136, v136, v137
	s_nop 1
	v_add_f32_dpp v136, v136, v136 quad_perm:[1,0,3,2] row_mask:0xf bank_mask:0xf
	s_nop 1
	v_add_f32_dpp v136, v136, v136 quad_perm:[2,3,0,1] row_mask:0xf bank_mask:0xf
	s_nop 1
	v_add_f32_dpp v136, v136, v136 row_half_mirror row_mask:0xf bank_mask:0xf
	s_nop 1
	v_add_f32_dpp v136, v136, v136 row_mirror row_mask:0xf bank_mask:0xf
	s_nop 1
	v_add_f32_dpp v136, v136, v136 row_bcast:15 row_mask:0xa bank_mask:0xf
	s_nop 1
	v_add_f32_dpp v136, v136, v136 row_bcast:31 row_mask:0xc bank_mask:0xf
	s_nop 1
	v_readlane_b32 s16, v136, 63
	s_nop 3
	v_fma_f32 v138, s16, v140, v141
	v_rsq_f32_e32 v138, v138
	s_nop 0
	v_mov_b32_e32 v139, v138
	v_pk_mul_f32 v[16:17], v[16:17], v[138:139]
	v_pk_mul_f32 v[18:19], v[18:19], v[138:139]
	v_pk_mul_f32 v[20:21], v[20:21], v[138:139]
	v_pk_mul_f32 v[22:23], v[22:23], v[138:139]
	v_pk_mul_f32 v[24:25], v[24:25], v[138:139]
	v_pk_mul_f32 v[26:27], v[26:27], v[138:139]
	v_pk_mul_f32 v[28:29], v[28:29], v[138:139]
	v_pk_mul_f32 v[30:31], v[30:31], v[138:139]
	v_pk_mul_f32 v[16:17], v[16:17], v[112:113]
	v_pk_mul_f32 v[18:19], v[18:19], v[114:115]
	v_pk_mul_f32 v[20:21], v[20:21], v[116:117]
	v_pk_mul_f32 v[22:23], v[22:23], v[118:119]
	v_pk_mul_f32 v[24:25], v[24:25], v[120:121]
	v_pk_mul_f32 v[26:27], v[26:27], v[122:123]
	v_pk_mul_f32 v[28:29], v[28:29], v[124:125]
	v_pk_mul_f32 v[30:31], v[30:31], v[126:127]
	global_store_dwordx4 v142, v[16:19], s[8:9] nt
	global_store_dwordx4 v142, v[20:23], s[8:9] offset:1024 nt
	global_store_dwordx4 v142, v[24:27], s[8:9] offset:2048 nt
	global_store_dwordx4 v142, v[28:31], s[8:9] offset:3072 nt
	s_add_u32 s8, s8, s10
	s_addc_u32 s9, s9, 0
